# combination of the individually validated small changes: static priority, top-k bounds + batched loads + 4/4 popcount split, rstd loads hoisted, W_uv and indexer-key operand layouts, DPP wave reductio
# speedup vs baseline: 1.0160x; 1.0160x over previous
; #define GAS __attribute__((address_space(1)))
; __device__ __forceinline__ unsigned pk2(float lo, float hi) { f32x2_t v = {lo, hi}; bf16x2_t b = __builtin_convertvector(v, bf16x2_t); return __builtin_bit_cast(unsigned, b); }
; __device__ __forceinline__ void prep_unit(const Args& a, LAS unsigned char* lds, int b, int kt, int tid) {
;     ...
;     const int key = tid >> 3, ch = tid & 7; const size_t row = (size_t)b * SEQ + kt * 64 + key;
;     const u32x4 d0 = *(const GAS u32x4*)(z + row * ZW + ZDC + 16 * ch), d1 = *(const GAS u32x4*)(z + row * ZW + ZDC + 16 * ch + 8);
;     const u32x4 k0 = *(const GAS u32x4*)(z + row * ZW + ZIK + 8 * ch);
;     float v[16]; float ss = 0.f;
; #pragma unroll
;     for (int i = 0; i < 4; ++i) { v[2 * i] = bflo(d0[i]); v[2 * i + 1] = bfhi(d0[i]); v[8 + 2 * i] = bflo(d1[i]); v[8 + 2 * i + 1] = bfhi(d1[i]); }
; #pragma unroll
;     for (int i = 0; i < 16; ++i) ss += v[i] * v[i];
;     ss += __shfl_xor(ss, 1); ss += __shfl_xor(ss, 2); ss += __shfl_xor(ss, 4);
;     const float r = rsqrtf(ss * (1.f / 128.f) + EPS);
;     unsigned short o[16];
;     u32x4 w0, w1;
; #pragma unroll
;     for (int i = 0; i < 4; ++i) { w0[i] = pk2(v[2 * i] * r, v[2 * i + 1] * r); w1[i] = pk2(v[8 + 2 * i] * r, v[8 + 2 * i + 1] * r);
;         o[2 * i] = (unsigned short)(w0[i] & 0xffffu); o[2 * i + 1] = (unsigned short)(w0[i] >> 16); o[8 + 2 * i] = (unsigned short)(w1[i] & 0xffffu); o[8 + 2 * i + 1] = (unsigned short)(w1[i] >> 16); }
;     GAS bf16* ckv = (GAS bf16*)(a.ws + WS_CKV);
;     *(GAS u32x4*)(ckv + row * 128 + 16 * ch) = w0; *(GAS u32x4*)(ckv + row * 128 + 16 * ch + 8) = w1;
; #pragma unroll
;     for (int i = 0; i < 16; ++i) tT[(16 * ch + i) * 72 + key] = o[i];
;     float kv[8]; float s2 = 0.f;
; #pragma unroll
;     for (int i = 0; i < 4; ++i) { kv[2 * i] = bflo(k0[i]); kv[2 * i + 1] = bfhi(k0[i]); }
; #pragma unroll
;     for (int i = 0; i < 8; ++i) s2 += kv[i] * kv[i];
;     s2 += __shfl_xor(s2, 1); s2 += __shfl_xor(s2, 2); s2 += __shfl_xor(s2, 4);
;     const float r2 = rsqrtf(s2 * (1.f / 64.f) + EPS);
;     u32x4 wk;
; #pragma unroll
;     for (int i = 0; i < 4; ++i) wk[i] = pk2(kv[2 * i] * r2, kv[2 * i + 1] * r2);
;     *(GAS u32x4*)((GAS bf16*)(a.ws + WS_IKN) + row * 64 + 8 * ch) = wk;
.LBB0_929:
	s_bfe_u32 s0, s13, 0x40005
	s_and_b32 s6, s8, 0x7c0
	s_lshl_b32 s7, s0, 11
	s_lshl_b32 s0, s0, 19
	s_or_b32 s7, s7, s6
	v_lshl_add_u64 v[24:25], v[6:7], 0, s[0:1]
	s_lshl_b32 s0, s6, 1
	v_add_u32_e32 v23, s7, v15
	v_lshl_add_u64 v[24:25], v[24:25], 0, s[0:1]
	v_mad_u64_u32 v[26:27], s[6:7], v23, s10, v[8:9]
	v_lshl_add_u64 v[36:37], v[24:25], 0, v[16:17]
	v_lshl_add_u64 v[24:25], v[26:27], 0, v[10:11]
	v_add_co_u32_e32 v40, vcc, 0x1000, v24
	v_lshl_add_u64 v[32:33], v[26:27], 0, v[12:13]
	v_lshl_add_u64 v[34:35], v[24:25], 0, s[2:3]
	v_addc_co_u32_e32 v41, vcc, 0, v25, vcc
	v_add_co_u32_e32 v32, vcc, s11, v32
	global_load_dwordx4 v[24:27], v[34:35], off offset:16
	global_load_dwordx4 v[28:31], v[40:41], off offset:2048
	v_addc_co_u32_e32 v33, vcc, 0, v33, vcc
	global_load_dwordx4 v[32:35], v[32:33], off offset:3328
	v_lshlrev_b32_e32 v0, 8, v23
	v_lshl_add_u64 v[38:39], v[2:3], 0, v[0:1]
	v_lshlrev_b32_e32 v0, 7, v23
	v_bfe_u32 v42, v23, 0, 4
	v_and_b32_e32 v0, 0xfffff800, v0
	v_lshl_or_b32 v0, v42, 4, v0
	v_lshl_add_u64 v[42:43], v[4:5], 0, v[0:1]
	s_add_i32 s13, s13, s84
	s_add_i32 s8, s8, s9
	s_cmpk_gt_i32 s13, 0x1ff
	s_waitcnt vmcnt(0)
	v_lshlrev_b32_e32 v40, 16, v27
	v_and_b32_e32 v53, 0xffff0000, v28
	v_lshlrev_b32_e32 v52, 16, v28
	v_mul_f32_e32 v0, v53, v53
	v_lshlrev_b32_e32 v48, 16, v29
	v_and_b32_e32 v49, 0xffff0000, v29
	v_lshlrev_b32_e32 v64, 16, v35
	v_and_b32_e32 v65, 0xffff0000, v35
	v_lshlrev_b32_e32 v66, 16, v34
	v_and_b32_e32 v67, 0xffff0000, v34
	v_lshlrev_b32_e32 v34, 16, v33
	v_and_b32_e32 v35, 0xffff0000, v33
	v_lshlrev_b32_e32 v68, 16, v32
	v_and_b32_e32 v69, 0xffff0000, v32
	v_pk_fma_f32 v[32:33], v[52:53], v[52:53], v[0:1] op_sel_hi:[1,1,0]
	v_mul_f32_e32 v58, v49, v49
	v_pk_fma_f32 v[32:33], v[48:49], v[48:49], v[32:33]
	v_and_b32_e32 v41, 0xffff0000, v27
	v_lshlrev_b32_e32 v46, 16, v26
	v_and_b32_e32 v47, 0xffff0000, v26
	v_lshlrev_b32_e32 v26, 16, v30
	v_and_b32_e32 v27, 0xffff0000, v30
	v_pk_add_f32 v[32:33], v[58:59], v[32:33] op_sel_hi:[0,1]
	v_mul_f32_e32 v60, v27, v27
	v_pk_fma_f32 v[32:33], v[26:27], v[26:27], v[32:33]
	v_lshlrev_b32_e32 v44, 16, v31
	v_and_b32_e32 v45, 0xffff0000, v31
	v_pk_add_f32 v[32:33], v[60:61], v[32:33] op_sel_hi:[0,1]
	v_lshlrev_b32_e32 v30, 16, v25
	v_and_b32_e32 v31, 0xffff0000, v25
	v_and_b32_e32 v25, 0xffff0000, v24
	v_mul_f32_e32 v62, v45, v45
	v_pk_fma_f32 v[32:33], v[44:45], v[44:45], v[32:33]
	v_lshlrev_b32_e32 v50, 16, v24
	v_and_b32_e32 v24, s0, v24
	v_mov_b32_e32 v51, v25
	v_pk_add_f32 v[32:33], v[62:63], v[32:33] op_sel_hi:[0,1]
	v_pk_mul_f32 v[24:25], v[24:25], v[24:25]
	v_pk_mul_f32 v[76:77], v[68:69], v[68:69]
	v_pk_fma_f32 v[32:33], v[50:51], v[50:51], v[32:33]
	v_pk_mul_f32 v[56:57], v[30:31], v[30:31]
	v_pk_mul_f32 v[74:75], v[34:35], v[34:35]
	v_mov_b32_e32 v24, v76
	v_pk_mov_b32 v[32:33], v[76:77], v[32:33] op_sel:[1,0]
	v_mov_b32_e32 v79, v56
	v_mov_b32_e32 v78, v74
	v_pk_add_f32 v[24:25], v[24:25], v[32:33]
	v_pk_mul_f32 v[54:55], v[46:47], v[46:47]
	v_pk_mul_f32 v[72:73], v[66:67], v[66:67]
	v_mov_b32_e32 v56, v75
	v_pk_add_f32 v[24:25], v[78:79], v[24:25]
	v_mov_b32_e32 v81, v54
	v_mov_b32_e32 v80, v72
	v_pk_add_f32 v[24:25], v[56:57], v[24:25]
	v_pk_mul_f32 v[28:29], v[40:41], v[40:41]
	v_pk_mul_f32 v[70:71], v[64:65], v[64:65]
	v_mov_b32_e32 v54, v73
	v_pk_add_f32 v[24:25], v[80:81], v[24:25]
	v_mov_b32_e32 v83, v28
	v_mov_b32_e32 v82, v70
	v_pk_add_f32 v[24:25], v[54:55], v[24:25]
	v_mov_b32_e32 v28, v71
	v_pk_add_f32 v[24:25], v[82:83], v[24:25]
	s_nop 0
	v_pk_add_f32 v[24:25], v[28:29], v[24:25]
	s_nop 0
	s_nop 0
	s_waitcnt lgkmcnt(0)
	s_nop 1
	v_mov_b32_dpp v29, v25 quad_perm:[1,0,3,2] row_mask:0xf bank_mask:0xf
	v_mov_b32_dpp v28, v24 quad_perm:[1,0,3,2] row_mask:0xf bank_mask:0xf
	v_pk_add_f32 v[24:25], v[24:25], v[28:29]
	s_nop 0
	s_nop 0
	s_waitcnt lgkmcnt(0)
	s_nop 1
	v_mov_b32_dpp v29, v25 quad_perm:[2,3,0,1] row_mask:0xf bank_mask:0xf
	v_mov_b32_dpp v28, v24 quad_perm:[2,3,0,1] row_mask:0xf bank_mask:0xf
	v_pk_add_f32 v[24:25], v[24:25], v[28:29]
	s_nop 0
	s_nop 0
	s_waitcnt lgkmcnt(0)
	s_nop 1
	v_mov_b32_dpp v29, v25 row_half_mirror row_mask:0xf bank_mask:0xf
	v_mov_b32_dpp v28, v24 row_half_mirror row_mask:0xf bank_mask:0xf
	v_pk_add_f32 v[24:25], v[24:25], v[28:29]
	s_nop 0
	v_pk_fma_f32 v[24:25], v[24:25], s[4:5], v[14:15] op_sel_hi:[1,1,0]
	s_nop 0
	v_mul_f32_e32 v0, 0x4b800000, v25
	v_mul_f32_e32 v23, 0x4b800000, v24
	v_cmp_gt_f32_e32 vcc, s12, v24
	v_cmp_gt_f32_e64 s[6:7], s12, v25
	s_nop 0
	v_cndmask_b32_e32 v23, v24, v23, vcc
	v_cndmask_b32_e64 v0, v25, v0, s[6:7]
	v_rsq_f32_e32 v0, v0
	v_rsq_f32_e32 v23, v23
	v_mul_f32_e32 v24, 0x45800000, v0
	v_mul_f32_e32 v25, 0x45800000, v23
	v_cndmask_b32_e64 v0, v0, v24, s[6:7]
	v_cndmask_b32_e32 v24, v23, v25, vcc
	v_pk_mul_f32 v[28:29], v[0:1], v[52:53] op_sel_hi:[0,1]
	v_pk_mul_f32 v[32:33], v[0:1], v[50:51] op_sel_hi:[0,1]
	v_pk_mul_f32 v[48:49], v[0:1], v[48:49] op_sel_hi:[0,1]
	v_pk_mul_f32 v[30:31], v[0:1], v[30:31] op_sel_hi:[0,1]
	v_pk_mul_f32 v[26:27], v[0:1], v[26:27] op_sel_hi:[0,1]
	v_pk_mul_f32 v[46:47], v[0:1], v[46:47] op_sel_hi:[0,1]
	v_pk_mul_f32 v[44:45], v[0:1], v[44:45] op_sel_hi:[0,1]
	v_pk_mul_f32 v[40:41], v[0:1], v[40:41] op_sel_hi:[0,1]
	v_pk_mul_f32 v[50:51], v[24:25], v[68:69] op_sel_hi:[0,1]
	v_pk_mul_f32 v[34:35], v[24:25], v[34:35] op_sel_hi:[0,1]
	v_pk_mul_f32 v[52:53], v[24:25], v[66:67] op_sel_hi:[0,1]
	v_pk_mul_f32 v[54:55], v[24:25], v[64:65] op_sel_hi:[0,1]
	v_cvt_pk_bf16_f32 v24, v28, v29
	v_cvt_pk_bf16_f32 v28, v32, v33
	v_cvt_pk_bf16_f32 v25, v48, v49
	v_cvt_pk_bf16_f32 v29, v30, v31
	v_cvt_pk_bf16_f32 v26, v26, v27
	v_cvt_pk_bf16_f32 v30, v46, v47
	v_cvt_pk_bf16_f32 v27, v44, v45
	v_cvt_pk_bf16_f32 v31, v40, v41
	v_cvt_pk_bf16_f32 v32, v50, v51
	v_cvt_pk_bf16_f32 v33, v34, v35
	v_cvt_pk_bf16_f32 v34, v52, v53
	v_cvt_pk_bf16_f32 v35, v54, v55
	global_store_dwordx4 v[38:39], v[24:27], off
	global_store_dwordx4 v[38:39], v[28:31], off offset:16
	ds_write_b16 v22, v24
	ds_write_b16_d16_hi v22, v24 offset:144
	ds_write_b16 v22, v25 offset:288
	ds_write_b16_d16_hi v22, v25 offset:432
	ds_write_b16 v22, v26 offset:576
	ds_write_b16_d16_hi v22, v26 offset:720
	ds_write_b16 v22, v27 offset:864
	ds_write_b16_d16_hi v22, v27 offset:1008
	ds_write_b16 v22, v28 offset:1152
	ds_write_b16_d16_hi v22, v28 offset:1296
	ds_write_b16 v22, v29 offset:1440
	ds_write_b16_d16_hi v22, v29 offset:1584
	ds_write_b16 v22, v30 offset:1728
	ds_write_b16_d16_hi v22, v30 offset:1872
	ds_write_b16 v22, v31 offset:2016
	ds_write_b16_d16_hi v22, v31 offset:2160
	global_store_dwordx4 v[42:43], v[32:35], off
	s_waitcnt lgkmcnt(0)
	s_barrier
	ds_read_b128 v[24:27], v21
	ds_read_b128 v[28:31], v21 offset:16
	s_waitcnt lgkmcnt(1)
	global_store_dwordx4 v[36:37], v[24:27], off
	s_waitcnt lgkmcnt(0)
	global_store_dwordx4 v[36:37], v[28:31], off offset:16
	s_barrier
	s_cbranch_scc0 .LBB0_929

; #define GAS __attribute__((address_space(1)))
; __device__ __forceinline__ f32x4 mfma16(bf16x8 a, bf16x8 b, f32x4 c) { return __builtin_amdgcn_mfma_f32_16x16x32_bf16(a, b, c, 0, 0, 0); }
; __device__ __forceinline__ void indexer_unit(const Args& a, LAS unsigned char* lds, LAS unsigned long long* maskl, int b, int qblk, int wave, int lane) {
;     ...
;     for (int kt = wave; kt < nkt; kt += 8) {
;         const int key = 16 * kt + fr;
;         const bf16x8 b0 = nb0, b1 = nb1;
;         { const int k2 = kt + 8 < nkt ? kt + 8 : kt; const GAS bf16* p = ikn + (rowb + 16 * k2 + fr) * 64 + 8 * fq; nb0 = *(const GAS bf16x8*)p; nb1 = *(const GAS bf16x8*)(p + 32); }
; #pragma unroll
;         for (int rt = 0; rt < 8; ++rt) {
;             f32x4 acc = {0.f, 0.f, 0.f, 0.f};
;             __builtin_amdgcn_s_setprio(1); acc = mfma16(af[rt][0], b0, acc); acc = mfma16(af[rt][1], b1, acc); __builtin_amdgcn_s_setprio(0);
;             float part = wv[rt][0] * fmaxf(acc[0], 0.f) + wv[rt][1] * fmaxf(acc[1], 0.f) + wv[rt][2] * fmaxf(acc[2], 0.f) + wv[rt][3] * fmaxf(acc[3], 0.f);
;             part += __shfl_xor(part, 16); part += 0.f;
;             if ((fq & 1) == 0) sc[(2 * rt + (fq >> 1)) * 2048 + key] = part;
;         }
.LBB0_1085:
	s_mov_b32 s11, s10
	s_add_i32 s10, s10, 8
	s_cmp_gt_u32 s10, s9
	s_cselect_b64 s[2:3], -1, 0
	s_and_b64 s[4:5], s[2:3], exec
	s_cselect_b32 s4, s11, s10
	v_lshl_add_u32 v74, s4, 4, v117
	v_mov_b32_e32 v75, v4
	v_lshlrev_b64 v[74:75], 7, v[74:75]
	v_lshl_add_u64 v[78:79], v[82:83], 0, v[74:75]
	global_load_dwordx4 v[74:77], v[78:79], off
	s_nop 0
	global_load_dwordx4 v[78:81], v[78:79], off offset:1024
	v_mfma_f32_16x16x32_bf16 v[128:131], v[0:3], v[70:73], 0
	v_mfma_f32_16x16x32_bf16 v[132:135], v[14:17], v[70:73], 0
	v_mfma_f32_16x16x32_bf16 v[136:139], v[18:21], v[70:73], 0
	v_mfma_f32_16x16x32_bf16 v[140:143], v[30:33], v[70:73], 0
	v_mfma_f32_16x16x32_bf16 v[144:147], v[34:37], v[70:73], 0
	v_mfma_f32_16x16x32_bf16 v[148:151], v[42:45], v[70:73], 0
	v_mfma_f32_16x16x32_bf16 v[152:155], v[54:57], v[70:73], 0
	v_mfma_f32_16x16x32_bf16 v[156:159], v[46:49], v[70:73], 0
	v_mfma_f32_16x16x32_bf16 v[128:131], v[6:9], v[66:69], v[128:131]
	v_mfma_f32_16x16x32_bf16 v[132:135], v[10:13], v[66:69], v[132:135]
	v_mfma_f32_16x16x32_bf16 v[136:139], v[22:25], v[66:69], v[136:139]
	v_mfma_f32_16x16x32_bf16 v[140:143], v[26:29], v[66:69], v[140:143]
	v_mfma_f32_16x16x32_bf16 v[144:147], v[38:41], v[66:69], v[144:147]
	v_mfma_f32_16x16x32_bf16 v[148:151], v[50:53], v[66:69], v[148:151]
	v_mfma_f32_16x16x32_bf16 v[152:155], v[58:61], v[66:69], v[152:155]
	v_mfma_f32_16x16x32_bf16 v[156:159], v[62:65], v[66:69], v[156:159]
	s_nop 1
	v_max_f32_e32 v160, 0, v128
	v_max_f32_e32 v168, 0, v129
	v_fma_f32 v168, v168, v86, 0
	v_max_f32_e32 v161, 0, v130
	v_fmac_f32_e32 v168, v160, v85
	v_max_f32_e32 v160, 0, v131
	v_fmac_f32_e32 v168, v161, v87
	v_fmac_f32_e32 v168, v160, v88
	v_max_f32_e32 v160, 0, v132
	v_max_f32_e32 v169, 0, v133
	v_fma_f32 v169, v169, v90, 0
	v_max_f32_e32 v161, 0, v134
	v_fmac_f32_e32 v169, v160, v89
	v_max_f32_e32 v160, 0, v135
	v_fmac_f32_e32 v169, v161, v91
	v_fmac_f32_e32 v169, v160, v92
	v_max_f32_e32 v160, 0, v136
	v_max_f32_e32 v170, 0, v137
	v_fma_f32 v170, v170, v94, 0
	v_max_f32_e32 v161, 0, v138
	v_fmac_f32_e32 v170, v160, v93
	v_max_f32_e32 v160, 0, v139
	v_fmac_f32_e32 v170, v161, v95
	v_fmac_f32_e32 v170, v160, v96
	v_max_f32_e32 v160, 0, v140
	v_max_f32_e32 v171, 0, v141
	v_fma_f32 v171, v171, v98, 0
	v_max_f32_e32 v161, 0, v142
	v_fmac_f32_e32 v171, v160, v97
	v_max_f32_e32 v160, 0, v143
	v_fmac_f32_e32 v171, v161, v99
	v_fmac_f32_e32 v171, v160, v100
	v_max_f32_e32 v160, 0, v144
	v_max_f32_e32 v172, 0, v145
	v_fma_f32 v172, v172, v102, 0
	v_max_f32_e32 v161, 0, v146
	v_fmac_f32_e32 v172, v160, v101
	v_max_f32_e32 v160, 0, v147
	v_fmac_f32_e32 v172, v161, v103
	v_fmac_f32_e32 v172, v160, v104
	v_max_f32_e32 v160, 0, v148
	v_max_f32_e32 v173, 0, v149
	v_fma_f32 v173, v173, v106, 0
	v_max_f32_e32 v161, 0, v150
	v_fmac_f32_e32 v173, v160, v105
	v_max_f32_e32 v160, 0, v151
	v_fmac_f32_e32 v173, v161, v107
	v_fmac_f32_e32 v173, v160, v108
	v_max_f32_e32 v160, 0, v152
	v_max_f32_e32 v174, 0, v153
	v_fma_f32 v174, v174, v110, 0
	v_max_f32_e32 v161, 0, v154
	v_fmac_f32_e32 v174, v160, v109
	v_max_f32_e32 v160, 0, v155
	v_fmac_f32_e32 v174, v161, v111
	v_fmac_f32_e32 v174, v160, v112
	v_max_f32_e32 v160, 0, v156
	v_max_f32_e32 v175, 0, v157
	v_fma_f32 v175, v175, v114, 0
	v_max_f32_e32 v161, 0, v158
	v_fmac_f32_e32 v175, v160, v113
	v_max_f32_e32 v160, 0, v159
	v_fmac_f32_e32 v175, v161, v115
	v_fmac_f32_e32 v175, v160, v116
	s_nop 0
	v_permlane16_swap_b32_e32 v168, v172
	v_permlane16_swap_b32_e32 v169, v173
	v_permlane16_swap_b32_e32 v170, v174
	v_permlane16_swap_b32_e32 v171, v175
	v_add_f32_e32 v168, v168, v172
	v_add_f32_e32 v169, v169, v173
	v_add_f32_e32 v170, v170, v174
	v_add_f32_e32 v171, v171, v175
	v_and_b32_e32 v160, 16, v252
	v_lshl_add_u32 v160, v160, 12, v119
	ds_write_b32 v160, v168
	ds_write_b32 v160, v169 offset:16384
	ds_write_b32 v160, v170 offset:32768
	ds_write_b32 v160, v171 offset:49152
	s_branch .LBB0_1084

; #define TK_GRP(g) { const int c0 = __popcll(__ballot(u[4 * (g)] >= cand)), c1 = __popcll(__ballot(u[4 * (g) + 1] >= cand)), c2 = __popcll(__ballot(u[4 * (g) + 2] >= cand)), c3 = __popcll(__ballot(u[4 * (g) + 3] >= cand)); cnt += (c0 + c1) + (c2 + c3); }
; __device__ __forceinline__ void indexer_unit(const Args& a, LAS unsigned char* lds, LAS unsigned long long* maskl, int b, int qblk, int wave, int lane) {
;     ...
;                 const unsigned cand = T | (1u << bit); int cnt = 0;
;     ...
;                 switch (ng) {
;                     case 8: TK_GRP(7) [[fallthrough]];
;                     case 7: TK_GRP(6) [[fallthrough]];
;                     case 6: TK_GRP(5) [[fallthrough]];
;                     case 5: TK_GRP(4) [[fallthrough]];
;                     case 4: TK_GRP(3) [[fallthrough]];
;                     case 3: TK_GRP(2) [[fallthrough]];
;                     case 2: TK_GRP(1) [[fallthrough]];
;                     default: TK_GRP(0)
;                 }
;     ...
;                 if (cnt >= 256) { T = cand; if (cnt == 256) { exact = true; break; } }
;             }
.Ltk_bit:
	s_lshl_b32 s12, 1, s11
	s_or_b32 s13, s10, s12
	s_cmp_gt_u32 s13, s18
	s_cbranch_scc1 .Ltk_nxt
	s_cmp_le_u32 s13, s23
	s_cbranch_scc1 .Ltk_acc
	v_mov_b32_e32 v24, 0
	v_cmp_le_u32_e64 s[24:25], s13, v32
	v_cmp_le_u32_e64 s[26:27], s13, v33
	v_cmp_le_u32_e64 s[28:29], s13, v34
	v_cmp_le_u32_e64 s[30:31], s13, v35
	v_cmp_le_u32_e64 s[34:35], s13, v36
	v_cmp_le_u32_e64 s[36:37], s13, v37
	v_cmp_le_u32_e64 s[38:39], s13, v38
	v_cmp_le_u32_e64 s[40:41], s13, v39
	s_bcnt1_i32_b64 s42, s[24:25]
	s_bcnt1_i32_b64 s43, s[26:27]
	s_bcnt1_i32_b64 s44, s[28:29]
	s_bcnt1_i32_b64 s45, s[30:31]
	s_bcnt1_i32_b64 s46, s[34:35]
	s_bcnt1_i32_b64 s47, s[36:37]
	s_bcnt1_i32_b64 s48, s[38:39]
	s_bcnt1_i32_b64 s49, s[40:41]
	s_add_i32 s14, s42, s43
	s_add_i32 s14, s14, s44
	s_add_i32 s14, s14, s45
	v_add_u32_e32 v24, s46, v24
	v_add_u32_e32 v24, s47, v24
	v_add_u32_e32 v24, s48, v24
	v_add_u32_e32 v24, s49, v24
	s_cmp_lt_u32 s21, 2
	s_cbranch_scc1 .Ltk_dec
	v_cmp_le_u32_e64 s[24:25], s13, v40
	v_cmp_le_u32_e64 s[26:27], s13, v41
	v_cmp_le_u32_e64 s[28:29], s13, v42
	v_cmp_le_u32_e64 s[30:31], s13, v43
	v_cmp_le_u32_e64 s[34:35], s13, v44
	v_cmp_le_u32_e64 s[36:37], s13, v45
	v_cmp_le_u32_e64 s[38:39], s13, v46
	v_cmp_le_u32_e64 s[40:41], s13, v47
	s_bcnt1_i32_b64 s42, s[24:25]
	s_bcnt1_i32_b64 s43, s[26:27]
	s_bcnt1_i32_b64 s44, s[28:29]
	s_bcnt1_i32_b64 s45, s[30:31]
	s_bcnt1_i32_b64 s46, s[34:35]
	s_bcnt1_i32_b64 s47, s[36:37]
	s_bcnt1_i32_b64 s48, s[38:39]
	s_bcnt1_i32_b64 s49, s[40:41]
	s_add_i32 s14, s14, s42
	s_add_i32 s14, s14, s43
	s_add_i32 s14, s14, s44
	s_add_i32 s14, s14, s45
	v_add_u32_e32 v24, s46, v24
	v_add_u32_e32 v24, s47, v24
	v_add_u32_e32 v24, s48, v24
	v_add_u32_e32 v24, s49, v24
	s_cmp_lt_u32 s21, 3
	s_cbranch_scc1 .Ltk_dec
	v_cmp_le_u32_e64 s[24:25], s13, v48
	v_cmp_le_u32_e64 s[26:27], s13, v49
	v_cmp_le_u32_e64 s[28:29], s13, v50
	v_cmp_le_u32_e64 s[30:31], s13, v51
	v_cmp_le_u32_e64 s[34:35], s13, v52
	v_cmp_le_u32_e64 s[36:37], s13, v53
	v_cmp_le_u32_e64 s[38:39], s13, v54
	v_cmp_le_u32_e64 s[40:41], s13, v55
	s_bcnt1_i32_b64 s42, s[24:25]
	s_bcnt1_i32_b64 s43, s[26:27]
	s_bcnt1_i32_b64 s44, s[28:29]
	s_bcnt1_i32_b64 s45, s[30:31]
	s_bcnt1_i32_b64 s46, s[34:35]
	s_bcnt1_i32_b64 s47, s[36:37]
	s_bcnt1_i32_b64 s48, s[38:39]
	s_bcnt1_i32_b64 s49, s[40:41]
	s_add_i32 s14, s14, s42
	s_add_i32 s14, s14, s43
	s_add_i32 s14, s14, s44
	s_add_i32 s14, s14, s45
	v_add_u32_e32 v24, s46, v24
	v_add_u32_e32 v24, s47, v24
	v_add_u32_e32 v24, s48, v24
	v_add_u32_e32 v24, s49, v24
	s_cmp_lt_u32 s21, 4
	s_cbranch_scc1 .Ltk_dec
	v_cmp_le_u32_e64 s[24:25], s13, v56
	v_cmp_le_u32_e64 s[26:27], s13, v57
	v_cmp_le_u32_e64 s[28:29], s13, v58
	v_cmp_le_u32_e64 s[30:31], s13, v59
	v_cmp_le_u32_e64 s[34:35], s13, v60
	v_cmp_le_u32_e64 s[36:37], s13, v61
	v_cmp_le_u32_e64 s[38:39], s13, v62
	v_cmp_le_u32_e64 s[40:41], s13, v63
	s_bcnt1_i32_b64 s42, s[24:25]
	s_bcnt1_i32_b64 s43, s[26:27]
	s_bcnt1_i32_b64 s44, s[28:29]
	s_bcnt1_i32_b64 s45, s[30:31]
	s_bcnt1_i32_b64 s46, s[34:35]
	s_bcnt1_i32_b64 s47, s[36:37]
	s_bcnt1_i32_b64 s48, s[38:39]
	s_bcnt1_i32_b64 s49, s[40:41]
	s_add_i32 s14, s14, s42
	s_add_i32 s14, s14, s43
	s_add_i32 s14, s14, s44
	s_add_i32 s14, s14, s45
	v_add_u32_e32 v24, s46, v24
	v_add_u32_e32 v24, s47, v24
	v_add_u32_e32 v24, s48, v24
	v_add_u32_e32 v24, s49, v24
